# stack + attention prologue: first item's Q fragments requested right behind its K-tile loads (v[220:251]), first loop pass enters behind the loop's Q loads
# baseline (speedup 1.0000x reference)
.LBB0_1129:
	v_add_co_u32_e32 v20, vcc, s21, v16
	s_not_b32 s63, s14
	s_nop 0
	v_addc_co_u32_e32 v21, vcc, 0, v17, vcc
	v_add_co_u32_e32 v24, vcc, s22, v16
	v_readlane_b32 s10, v254, 49
	s_nop 0
	v_addc_co_u32_e32 v25, vcc, 0, v17, vcc
	v_add_co_u32_e32 v28, vcc, s23, v16
	global_load_dwordx4 v[20:23], v[20:21], off
	s_nop 0
	global_load_dwordx4 v[24:27], v[24:25], off
	v_addc_co_u32_e32 v29, vcc, 0, v17, vcc
	v_add_co_u32_e32 v32, vcc, s24, v16
	s_movk_i32 s14, 0xf0
	s_nop 0
	v_addc_co_u32_e32 v33, vcc, 0, v17, vcc
	v_add_co_u32_e32 v36, vcc, s15, v16
	global_load_dwordx4 v[28:31], v[28:29], off
	s_nop 0
	global_load_dwordx4 v[32:35], v[32:33], off
	v_addc_co_u32_e32 v37, vcc, 0, v17, vcc
	v_add_co_u32_e32 v40, vcc, s18, v16
	v_readlane_b32 s11, v254, 50
	s_nop 0
	v_addc_co_u32_e32 v41, vcc, 0, v17, vcc
	v_add_co_u32_e32 v44, vcc, s19, v16
	global_load_dwordx4 v[36:39], v[36:37], off
	s_nop 0
	global_load_dwordx4 v[40:43], v[40:41], off
	v_addc_co_u32_e32 v45, vcc, 0, v17, vcc
	v_add_co_u32_e32 v16, vcc, s20, v16
	s_and_b64 s[10:11], s[10:11], exec
	s_nop 0
	v_addc_co_u32_e32 v17, vcc, 0, v17, vcc
	global_load_dwordx4 v[44:47], v[44:45], off
	s_nop 0
	global_load_dwordx4 v[48:51], v[16:17], off
	v_xor_b32_e32 v16, v128, v19
	v_lshlrev_b32_e32 v17, 8, v128
	v_lshlrev_b32_e32 v54, 4, v16
	v_and_or_b32 v17, v54, s14, v17
	s_load_dwordx2 s[14:15], s[8:9], 0x70
	s_cselect_b32 s10, 0, 8
	s_lshl_b32 s11, 1, s40
	s_add_u32 s20, s4, s13
	s_addc_u32 s21, s5, 0
	s_waitcnt lgkmcnt(0)
	s_add_u32 s22, s14, 0x1100000
	v_cvt_f32_u32_e32 v152, s11
	s_addc_u32 s23, s15, 0
	s_lshl_b32 s11, s12, 4
	v_and_b32_e32 v149, 63, v19
	s_or_b32 s11, s11, 1
	s_cmp_gt_i32 s28, 0
	v_cmp_gt_u32_e64 s[42:43], 32, v149
	s_cselect_b64 s[24:25], -1, 0
	s_add_i32 s18, s40, 13
	s_and_b64 s[26:27], s[0:1], s[42:43]
	s_cmp_gt_i32 s28, 1
	s_cselect_b64 s[28:29], -1, 0
	s_add_i32 s0, s40, 12
	s_lshl_b64 s[60:61], 1, s0
	v_writelane_b32 v254, s60, 52
	v_bfe_u32 v53, v19, 5, 1
	v_and_b32_e32 v150, 31, v19
	v_writelane_b32 v254, s61, 53
	s_lshl_b64 s[60:61], 2, s0
	v_writelane_b32 v254, s60, 54
	v_ashrrev_i32_e32 v130, 2, v19
	v_lshlrev_b32_e32 v19, 4, v19
	v_lshlrev_b32_e32 v138, 4, v53
	v_writelane_b32 v254, s61, 55
	s_lshl_b64 s[60:61], 3, s0
	v_and_b32_e32 v16, 48, v19
	v_add_u32_e32 v151, 0, v17
	v_lshl_add_u64 v[132:133], s[6:7], 0, v[138:139]
	v_readlane_b32 s6, v253, 56
	v_mov_b32_e32 v17, v139
	v_writelane_b32 v254, s60, 56
	s_ashr_i32 s98, s58, 6
	s_ashr_i32 s99, s98, 31
	s_lshl_b64 s[98:99], s[98:99], 14
	s_and_b32 s100, s58, 63
	s_lshr_b32 s101, s100, s62
	s_mul_i32 s101, s101, s41
	s_add_u32 s98, s98, s101
	s_addc_u32 s99, s99, 0
	s_and_b32 s100, s100, s63
	s_lshl_b32 s100, s100, 8
	v_readlane_b32 s101, v253, 56
	v_mov_b32_e32 v219, 0
	s_nop 1
	s_add_i32 s100, s100, s101
	v_or_b32_e32 v218, s100, v150
	v_lshl_add_u64 v[218:219], s[98:99], 0, v[218:219]
	v_lshlrev_b64 v[218:219], 8, v[218:219]
	v_lshl_add_u64 v[218:219], v[132:133], 0, v[218:219]
	global_load_dwordx4 v[220:223], v[218:219], off
	global_load_dwordx4 v[224:227], v[218:219], off offset:32
	global_load_dwordx4 v[228:231], v[218:219], off offset:64
	global_load_dwordx4 v[232:235], v[218:219], off offset:96
	global_load_dwordx4 v[236:239], v[218:219], off offset:128
	global_load_dwordx4 v[240:243], v[218:219], off offset:160
	global_load_dwordx4 v[244:247], v[218:219], off offset:192
	global_load_dwordx4 v[248:251], v[218:219], off offset:224
	s_waitcnt vmcnt(16)
	ds_write_b128 v151, v[0:3]
	ds_write_b128 v151, v[8:11] offset:8192
	ds_write_b128 v151, v[4:7] offset:16384
	ds_write_b128 v151, v[12:15] offset:24576
	v_or_b32_e32 v2, s6, v150
	v_lshl_add_u64 v[0:1], s[14:15], 0, v[16:17]
	s_mov_b64 s[6:7], 0xc000000
	v_readlane_b32 s1, v253, 51
	v_writelane_b32 v254, s61, 57
	s_lshl_b64 s[60:61], 4, s0
	v_lshl_add_u64 v[134:135], v[0:1], 0, s[6:7]
	v_mov_b32_e32 v0, s1
	s_movk_i32 s1, 0x210
	v_writelane_b32 v254, s60, 58
	v_lshlrev_b32_e32 v52, 3, v18
	v_mad_u32_u24 v4, v150, s1, v0
	v_readlane_b32 s1, v253, 47
	v_writelane_b32 v254, s61, 59
	s_lshl_b64 s[60:61], 5, s0
	s_movk_i32 s50, 0x310
	v_lshl_add_u32 v160, v150, 2, s1
	v_lshlrev_b32_e32 v0, 1, v52
	v_mov_b32_e32 v1, v139
	v_readlane_b32 s1, v253, 53
	v_writelane_b32 v254, s60, 60
	v_mul_lo_u32 v55, v130, s50
	v_lshl_add_u64 v[136:137], s[4:5], 0, v[0:1]
	v_lshl_add_u32 v0, v2, 8, 0
	v_xor_b32_e32 v1, v53, v18
	v_bitop3_b32 v2, v53, v18, 2 bitop3:0x36
	v_bitop3_b32 v5, v53, v18, 4 bitop3:0x36
	v_bitop3_b32 v6, v53, v18, 6 bitop3:0x36
	v_bitop3_b32 v7, v53, v18, 8 bitop3:0x36
	v_bitop3_b32 v8, v53, v18, 10 bitop3:0x36
	v_bitop3_b32 v9, v53, v18, 12 bitop3:0x36
	v_bitop3_b32 v10, v53, v18, 14 bitop3:0x36
	v_add_u32_e32 v12, s1, v138
	v_writelane_b32 v254, s61, 61
	s_lshl_b64 s[60:61], 6, s0
	s_lshl_b64 s[0:1], 7, s0
	v_or_b32_e32 v19, 0x80, v150
	v_lshlrev_b32_e32 v157, 2, v53
	v_add_u32_e32 v3, 0, v55
	v_lshlrev_b32_e32 v1, 4, v1
	v_lshlrev_b32_e32 v2, 4, v2
	v_lshlrev_b32_e32 v5, 4, v5
	v_lshlrev_b32_e32 v6, 4, v6
	v_lshlrev_b32_e32 v7, 4, v7
	v_lshlrev_b32_e32 v8, 4, v8
	v_lshlrev_b32_e32 v9, 4, v9
	v_lshlrev_b32_e32 v10, 4, v10
	s_lshl_b64 s[4:5], 32, s53
	s_lshl_b64 s[12:13], 64, s53
	s_lshl_b64 s[14:15], 0x60, s53
	s_lshl_b64 s[44:45], 0x80, s53
	s_lshl_b64 s[46:47], 0xa0, s53
	s_lshl_b64 s[48:49], 0xc0, s53
	s_lshl_b64 s[72:73], 0xe0, s53
	s_lshl_b64 s[74:75], 0x100, s53
	s_lshl_b64 s[76:77], 0x120, s53
	s_lshl_b64 s[78:79], 0x140, s53
	s_lshl_b64 s[80:81], 0x160, s53
	v_mul_u32_u24_e32 v11, 0x310, v150
	v_mad_u32_u24 v13, v150, s50, v174
	v_writelane_b32 v254, s60, 62
	v_writelane_b32 v255, s0, 0
	s_mov_b32 s51, 0x16000
	v_add_u32_e32 v153, 0x10000, v151
	v_add_u32_e32 v154, 0x12000, v151
	v_add_u32_e32 v155, 0x14000, v151
	v_add_u32_e32 v156, 0x16000, v151
	v_sub_u32_e32 v158, v19, v157
	v_cvt_f32_ubyte0_e32 v159, v157
	v_ashrrev_i32_e32 v131, 31, v130
	s_lshl_b64 s[30:31], 1, s18
	s_lshl_b64 s[54:55], 2, s18
	s_lshl_b64 s[34:35], 3, s18
	s_lshl_b64 s[36:37], 4, s18
	s_lshl_b64 s[38:39], 5, s18
	s_lshl_b64 s[6:7], 6, s18
	s_lshl_b64 s[18:19], 7, s18
	v_writelane_b32 v254, s61, 63
	v_writelane_b32 v255, s1, 1
	s_lshl_b64 s[0:1], 0x2000, s40
	s_lshl_b32 s60, s4, 1
	s_lshl_b32 s64, s12, 1
	s_lshl_b32 s66, s14, 1
	s_lshl_b32 s56, s44, 1
	s_lshl_b32 s68, s46, 1
	s_lshl_b32 s70, s48, 1
	s_lshl_b32 s72, s72, 1
	s_lshl_b32 s74, s74, 1
	s_lshl_b32 s76, s76, 1
	s_lshl_b32 s78, s78, 1
	s_lshl_b32 s80, s80, 1
	v_add_u32_e32 v161, v3, v16
	v_add_u32_e32 v162, v4, v138
	v_add_u32_e32 v163, v0, v1
	v_add_u32_e32 v164, v0, v2
	v_add_u32_e32 v165, v0, v5
	v_add_u32_e32 v166, v0, v6
	v_add_u32_e32 v167, v0, v7
	v_add_u32_e32 v168, v0, v8
	v_add_u32_e32 v169, v0, v9
	v_add_u32_e32 v170, v0, v10
	v_add_u32_e32 v171, v12, v11
	v_add_u32_e32 v191, v12, v13
	s_lshl_b64 s[82:83], 0x4000, s40
	s_lshl_b64 s[84:85], 0x6000, s40
	s_lshl_b64 s[86:87], 0x8000, s40
	s_lshl_b64 s[88:89], 0xa000, s40
	s_lshl_b64 s[90:91], 0xc000, s40
	s_lshl_b64 s[92:93], 0xe000, s40
	s_waitcnt vmcnt(15)
	ds_write_b128 v151, v[20:23] offset:32768
	s_waitcnt vmcnt(14)
	ds_write_b128 v151, v[24:27] offset:40960
	s_waitcnt vmcnt(13)
	ds_write_b128 v151, v[28:31] offset:49152
	s_waitcnt vmcnt(12)
	ds_write_b128 v151, v[32:35] offset:57344
	s_waitcnt vmcnt(11)
	ds_write_b128 v153, v[36:39]
	s_waitcnt vmcnt(10)
	ds_write_b128 v154, v[40:43]
	s_waitcnt vmcnt(9)
	ds_write_b128 v155, v[44:47]
	s_waitcnt vmcnt(8)
	ds_write_b128 v156, v[48:51]
.Lq0_first:
	s_ashr_i32 s44, s58, 6
	s_and_b32 s4, s58, 63
	s_add_i32 s46, s44, s10
	s_lshr_b32 s47, s4, s62
	s_and_b32 s5, s4, s63
	s_add_i32 s4, s11, s46
	v_cvt_f32_i32_e32 v0, s4
	s_lshl_b32 s61, s5, 8
	v_readlane_b32 s4, v253, 56
	s_ashr_i32 s45, s44, 31
	v_mul_f32_e32 v0, 0xbe2aaaab, v0
	v_exp_f32_e32 v0, v0
	s_add_i32 s4, s61, s4
	s_lshl_b64 s[12:13], s[44:45], 14
	s_mul_i32 s45, s47, s41
	s_add_u32 s12, s12, s45
	v_or_b32_e32 v138, s4, v150
	s_addc_u32 s13, s13, 0
	v_mul_f32_e32 v2, v0, v152
	v_lshl_add_u64 v[0:1], s[12:13], 0, v[138:139]
	v_lshlrev_b64 v[0:1], 8, v[0:1]
	v_mov_b32_e32 v93, v158
	v_lshl_add_u64 v[0:1], v[132:133], 0, v[0:1]
	s_waitcnt vmcnt(0)
	v_mov_b32_e32 v44, v220
	v_mov_b32_e32 v45, v221
	v_mov_b32_e32 v46, v222
	v_mov_b32_e32 v47, v223
	v_mov_b32_e32 v40, v224
	v_mov_b32_e32 v41, v225
	v_mov_b32_e32 v42, v226
	v_mov_b32_e32 v43, v227
	v_mov_b32_e32 v36, v228
	v_mov_b32_e32 v37, v229
	v_mov_b32_e32 v38, v230
	v_mov_b32_e32 v39, v231
	v_mov_b32_e32 v32, v232
	v_mov_b32_e32 v33, v233
	v_mov_b32_e32 v34, v234
	v_mov_b32_e32 v35, v235
	v_mov_b32_e32 v28, v236
	v_mov_b32_e32 v29, v237
	v_mov_b32_e32 v30, v238
	v_mov_b32_e32 v31, v239
	v_mov_b32_e32 v24, v240
	v_mov_b32_e32 v25, v241
	v_mov_b32_e32 v26, v242
	v_mov_b32_e32 v27, v243
	v_mov_b32_e32 v20, v244
	v_mov_b32_e32 v21, v245
	v_mov_b32_e32 v22, v246
	v_mov_b32_e32 v23, v247
	v_mov_b32_e32 v16, v248
	v_mov_b32_e32 v17, v249
	v_mov_b32_e32 v18, v250
	v_mov_b32_e32 v19, v251
	s_branch .Lq0_join

.Lq0_join:
	s_cmpk_gt_u32 s4, 0x7f
	s_mov_b32 s50, s94
	v_mul_f32_e32 v92, 0x3fb8aa3b, v2
	v_mov_b32_e32 v48, 0xf149f2ca
	s_cselect_b64 s[48:49], -1, 0
	s_cmpk_lt_u32 s4, 0x80
	v_mov_b32_e32 v84, 0xf149f2ca
	v_mov_b32_e32 v85, 0xf149f2ca
	v_mov_b32_e32 v100, 0xf149f2ca
	v_mov_b32_e32 v102, 0xf149f2ca
	v_mov_b32_e32 v101, 0xf149f2ca
	v_mov_b32_e32 v104, 0xf149f2ca
	v_mov_b32_e32 v103, 0xf149f2ca
	v_mov_b32_e32 v106, 0xf149f2ca
	v_mov_b32_e32 v105, 0xf149f2ca
	v_mov_b32_e32 v108, 0xf149f2ca
	v_mov_b32_e32 v107, 0xf149f2ca
	v_mov_b32_e32 v110, 0xf149f2ca
	v_mov_b32_e32 v109, 0xf149f2ca
	v_mov_b32_e32 v112, 0xf149f2ca
	v_mov_b32_e32 v111, 0xf149f2ca
	v_mov_b32_e32 v114, 0xf149f2ca
	v_mov_b32_e32 v113, 0xf149f2ca
	s_waitcnt lgkmcnt(0)
	s_barrier
	s_cbranch_scc1 .LBB0_1133
	ds_read_b128 v[0:3], v163
	ds_read_b128 v[50:53], v164
	s_mov_b32 s12, 2.0
	s_mov_b32 s13, 0x40400000
	v_cmp_gt_i32_e32 vcc, s67, v93
	s_waitcnt vmcnt(7) lgkmcnt(1)
	v_mfma_f32_32x32x16_bf16 v[0:15], v[0:3], v[44:47], 0
	s_waitcnt vmcnt(6) lgkmcnt(0)
	v_mfma_f32_32x32x16_bf16 v[0:15], v[50:53], v[40:43], v[0:15]
	ds_read_b128 v[50:53], v165
	ds_read_b128 v[54:57], v166
	s_waitcnt vmcnt(5) lgkmcnt(1)
	v_mfma_f32_32x32x16_bf16 v[0:15], v[50:53], v[36:39], v[0:15]
	s_waitcnt vmcnt(4) lgkmcnt(0)
	v_mfma_f32_32x32x16_bf16 v[0:15], v[54:57], v[32:35], v[0:15]
	ds_read_b128 v[50:53], v167
	ds_read_b128 v[54:57], v168
	s_waitcnt vmcnt(3) lgkmcnt(1)
	v_mfma_f32_32x32x16_bf16 v[0:15], v[50:53], v[28:31], v[0:15]
	s_waitcnt vmcnt(2) lgkmcnt(0)
	v_mfma_f32_32x32x16_bf16 v[0:15], v[54:57], v[24:27], v[0:15]
	ds_read_b128 v[50:53], v169
	ds_read_b128 v[54:57], v170
	s_waitcnt vmcnt(1) lgkmcnt(1)
	v_mfma_f32_32x32x16_bf16 v[0:15], v[50:53], v[20:23], v[0:15]
	s_waitcnt vmcnt(0) lgkmcnt(0)
	v_mfma_f32_32x32x16_bf16 v[0:15], v[54:57], v[16:19], v[0:15]
	s_nop 11
	v_pk_fma_f32 v[2:3], v[92:93], s[12:13], v[2:3] op_sel_hi:[0,1,1]
	s_mov_b32 s12, 0x41000000
	s_mov_b32 s13, 0x41100000
	v_pk_fma_f32 v[4:5], v[92:93], s[12:13], v[4:5] op_sel_hi:[0,1,1]
	s_mov_b32 s12, 0x41200000
	s_mov_b32 s13, 0x41300000
	v_pk_fma_f32 v[6:7], v[92:93], s[12:13], v[6:7] op_sel_hi:[0,1,1]
	s_mov_b32 s12, 0x41800000
	s_mov_b32 s13, 0x41880000
	v_pk_fma_f32 v[8:9], v[92:93], s[12:13], v[8:9] op_sel_hi:[0,1,1]
	s_mov_b32 s12, 0x41900000
	s_mov_b32 s13, 0x41980000
	v_pk_fma_f32 v[10:11], v[92:93], s[12:13], v[10:11] op_sel_hi:[0,1,1]
	s_mov_b32 s12, 0x41c00000
	s_mov_b32 s13, 0x41c80000
	v_pk_fma_f32 v[12:13], v[92:93], s[12:13], v[12:13] op_sel_hi:[0,1,1]
	s_mov_b32 s12, 0x41d00000
	s_mov_b32 s13, 0x41d80000
	v_fma_f32 v49, 0, v92, v0
	v_add_f32_e32 v50, v92, v1
	v_pk_fma_f32 v[0:1], v[92:93], s[12:13], v[14:15] op_sel_hi:[0,1,1]
	s_movk_i32 s12, 0x82
	v_cndmask_b32_e32 v85, v175, v49, vcc
	v_cmp_gt_i32_e32 vcc, s12, v93
	s_movk_i32 s12, 0x84
	s_nop 0
	v_cndmask_b32_e32 v100, v175, v50, vcc
	v_cmp_gt_i32_e32 vcc, s12, v93
	s_movk_i32 s12, 0x83
	s_nop 0
	v_cndmask_b32_e32 v101, v175, v3, vcc
	v_cmp_gt_i32_e32 vcc, s12, v93
	s_movk_i32 s12, 0x8a
	s_nop 0
	v_cndmask_b32_e32 v102, v175, v2, vcc
	v_cmp_gt_i32_e32 vcc, s12, v93
	s_movk_i32 s12, 0x89
	s_nop 0
	v_cndmask_b32_e32 v103, v175, v5, vcc
	v_cmp_gt_i32_e32 vcc, s12, v93
	s_movk_i32 s12, 0x8c
	s_nop 0
	v_cndmask_b32_e32 v104, v175, v4, vcc
	v_cmp_gt_i32_e32 vcc, s12, v93
	s_movk_i32 s12, 0x8b
	s_nop 0
	v_cndmask_b32_e32 v105, v175, v7, vcc
	v_cmp_gt_i32_e32 vcc, s12, v93
	s_movk_i32 s12, 0x92
	s_nop 0
	v_cndmask_b32_e32 v106, v175, v6, vcc
	v_cmp_gt_i32_e32 vcc, s12, v93
	s_movk_i32 s12, 0x91
	s_nop 0
	v_cndmask_b32_e32 v107, v175, v9, vcc
	v_cmp_gt_i32_e32 vcc, s12, v93
	s_movk_i32 s12, 0x94
	s_nop 0
	v_cndmask_b32_e32 v108, v175, v8, vcc
	v_cmp_gt_i32_e32 vcc, s12, v93
	s_movk_i32 s12, 0x93
	s_nop 0
	v_cndmask_b32_e32 v109, v175, v11, vcc
	v_cmp_gt_i32_e32 vcc, s12, v93
	s_movk_i32 s12, 0x9a
	s_nop 0
	v_cndmask_b32_e32 v110, v175, v10, vcc
	v_cmp_gt_i32_e32 vcc, s12, v93
	s_movk_i32 s12, 0x99
	s_nop 0
	v_cndmask_b32_e32 v111, v175, v13, vcc
	v_cmp_gt_i32_e32 vcc, s12, v93
	s_movk_i32 s12, 0x9c
	s_nop 0
	v_cndmask_b32_e32 v112, v175, v12, vcc
	v_cmp_gt_i32_e32 vcc, s12, v93
	s_mov_b32 s12, 0xf149f2ca
	s_nop 0
	v_cndmask_b32_e32 v113, v175, v1, vcc
	v_max3_f32 v1, v85, s12, v100
	v_max3_f32 v1, v1, v102, v101
	v_max3_f32 v1, v1, v104, v103
	v_max3_f32 v1, v1, v106, v105
	v_max3_f32 v1, v1, v108, v107
	s_movk_i32 s12, 0x9b
	v_max3_f32 v1, v1, v110, v109
	v_cmp_gt_i32_e32 vcc, s12, v93
	v_max3_f32 v1, v1, v112, v111
	s_nop 0
	v_cndmask_b32_e32 v114, v175, v0, vcc
	v_max3_f32 v84, v1, v114, v113
